# k17_pack
# speedup vs baseline: 1.1050x; 1.0081x over previous
; DI unsigned pack2(float a, float b) { return (unsigned)f2bf(a) | ((unsigned)f2bf(b) << 16); }
; DI f32x16 mfma32(bf16x8 a, bf16x8 b, f32x16 c) { return __builtin_amdgcn_mfma_f32_32x32x16_bf16(a, b, c, 0, 0, 0); }
; DI bf16x8 pack8(float a0, float a1, float a2, float a3, float a4, float a5, float a6, float a7) {
;   u32x4 p; p[0] = pack2(a0, a1); p[1] = pack2(a2, a3); p[2] = pack2(a4, a5); p[3] = pack2(a6, a7);
;   return __builtin_bit_cast(bf16x8, p);
; }
; template <bool MLA>
; DI void attn_task(const Params& p, char* smem, int b, int head, int qt) {
;     ...
; #pragma unroll
;       for (int k2 = 0; k2 < 2; ++k2)
; #pragma unroll
;         for (int i = 0; i < 16; ++i) { const float pv = __builtin_amdgcn_exp2f(s[k2][i] - mn); l += pv; s[k2][i] = pv; }
; #pragma unroll
;       for (int k2 = 0; k2 < 2; ++k2)
; #pragma unroll
;         for (int st = 0; st < 2; ++st) {
;           const bf16x8 pb = pack8(s[k2][8 * st + 0], s[k2][8 * st + 1], s[k2][8 * st + 2], s[k2][8 * st + 3],
;                                   s[k2][8 * st + 4], s[k2][8 * st + 5], s[k2][8 * st + 6], s[k2][8 * st + 7]);
; #pragma unroll
;           for (int dt = 0; dt < 2; ++dt) {
;             const bf16x8 va = frag_tr_perm(Vs, VLD, k2 * 32 + st * 16, dt * 32, lane);
;             oacc[dt] = mfma32(va, pb, oacc[dt]);
;           }
;         }
.LBB0_368:
	v_sub_f32_e32 v48, v48, v106
	v_exp_f32_e32 v48, v48
	v_sub_f32_e32 v49, v49, v106
	v_sub_f32_e32 v50, v50, v106
	v_exp_f32_e32 v49, v49
	v_exp_f32_e32 v50, v50
	v_sub_f32_e32 v51, v51, v106
	v_exp_f32_e32 v51, v51
	v_sub_f32_e32 v52, v52, v106
	v_sub_f32_e32 v32, v32, v106
	v_add_f32_e32 v105, v105, v48
	v_exp_f32_e32 v52, v52
	v_sub_f32_e32 v53, v53, v106
	v_exp_f32_e32 v107, v32
	v_sub_f32_e32 v32, v33, v106
	v_add_f32_e32 v105, v49, v105
	v_exp_f32_e32 v53, v53
	v_sub_f32_e32 v54, v54, v106
	v_exp_f32_e32 v133, v32
	v_sub_f32_e32 v32, v34, v106
	v_add_f32_e32 v105, v50, v105
	v_exp_f32_e32 v54, v54
	v_sub_f32_e32 v55, v55, v106
	v_exp_f32_e32 v134, v32
	v_sub_f32_e32 v32, v35, v106
	v_add_f32_e32 v105, v51, v105
	v_exp_f32_e32 v55, v55
	v_exp_f32_e32 v135, v32
	v_sub_f32_e32 v32, v36, v106
	v_add_f32_e32 v105, v52, v105
	v_exp_f32_e32 v136, v32
	v_cvt_pk_bf16_f32 v34, v51, s0
	v_add_u32_e32 v137, v119, v123
	v_add_f32_e32 v105, v53, v105
	v_cvt_pk_bf16_f32 v32, v48, v49
	v_cvt_pk_bf16_f32 v33, v50, s0
	v_lshlrev_b32_e32 v34, 16, v34
	ds_read_b64_tr_b16 v[48:49], v137 offset:9216
	ds_read_b64_tr_b16 v[50:51], v137 offset:10752
	v_add_f32_e32 v105, v54, v105
	v_or_b32_sdwa v33, v34, v33 dst_sel:DWORD dst_unused:UNUSED_PAD src0_sel:DWORD src1_sel:WORD_0
	v_add_f32_e32 v105, v55, v105
	v_sub_f32_e32 v57, v57, v106
	v_sub_f32_e32 v36, v37, v106
	v_cvt_pk_bf16_f32 v34, v52, v53
	v_cvt_pk_bf16_f32 v35, v54, s0
	v_cvt_pk_bf16_f32 v37, v55, s0
	ds_read_b64_tr_b16 v[54:55], v137 offset:10816
	ds_read_b64_tr_b16 v[52:53], v137 offset:9280
	v_sub_f32_e32 v56, v56, v106
	v_exp_f32_e32 v57, v57
	v_sub_f32_e32 v59, v59, v106
	v_lshlrev_b32_e32 v37, 16, v37
	v_exp_f32_e32 v56, v56
	v_sub_f32_e32 v58, v58, v106
	v_exp_f32_e32 v59, v59
	v_sub_f32_e32 v61, v61, v106
	v_or_b32_sdwa v35, v37, v35 dst_sel:DWORD dst_unused:UNUSED_PAD src0_sel:DWORD src1_sel:WORD_0
	v_exp_f32_e32 v58, v58
	v_sub_f32_e32 v60, v60, v106
	v_exp_f32_e32 v61, v61
	v_sub_f32_e32 v63, v63, v106
	s_waitcnt lgkmcnt(2)
	v_mfma_f32_32x32x16_bf16 v[16:31], v[48:51], v[32:35], v[16:31]
	v_exp_f32_e32 v138, v36
	v_sub_f32_e32 v36, v38, v106
	v_exp_f32_e32 v60, v60
	v_sub_f32_e32 v62, v62, v106
	v_exp_f32_e32 v63, v63
	v_exp_f32_e32 v139, v36
	v_sub_f32_e32 v36, v39, v106
	v_exp_f32_e32 v62, v62
	v_exp_f32_e32 v140, v36
	v_sub_f32_e32 v36, v40, v106
	s_waitcnt lgkmcnt(0)
	v_mfma_f32_32x32x16_bf16 v[0:15], v[52:55], v[32:35], v[0:15]
	v_exp_f32_e32 v141, v36
	ds_read_b64_tr_b16 v[36:37], v137 offset:12288
	ds_read_b64_tr_b16 v[38:39], v137 offset:13824
	v_cvt_pk_bf16_f32 v32, v56, v57
	v_cvt_pk_bf16_f32 v33, v58, v59
	ds_read_b64_tr_b16 v[50:51], v137 offset:13888
	ds_read_b64_tr_b16 v[48:49], v137 offset:12352
	v_cvt_pk_bf16_f32 v34, v60, v61
	v_cvt_pk_bf16_f32 v35, v62, v63
	s_waitcnt lgkmcnt(2)
	s_nop 0
	v_mfma_f32_32x32x16_bf16 v[16:31], v[36:39], v[32:35], v[16:31]
	v_sub_f32_e32 v36, v41, v106
	v_exp_f32_e32 v52, v36
	v_sub_f32_e32 v36, v42, v106
	v_exp_f32_e32 v53, v36
	v_sub_f32_e32 v36, v43, v106
	v_exp_f32_e32 v54, v36
	ds_read_b64_tr_b16 v[36:37], v137 offset:15360
	ds_read_b64_tr_b16 v[38:39], v137 offset:16896
	s_waitcnt lgkmcnt(2)
	v_mfma_f32_32x32x16_bf16 v[0:15], v[48:51], v[32:35], v[0:15]
	v_cvt_pk_bf16_f32 v32, v107, v133
	v_cvt_pk_bf16_f32 v33, v134, v135
	v_cvt_pk_bf16_f32 v34, v136, v138
	v_cvt_pk_bf16_f32 v35, v139, v140
	ds_read_b64_tr_b16 v[42:43], v137 offset:16960
	ds_read_b64_tr_b16 v[40:41], v137 offset:15424
	s_waitcnt lgkmcnt(2)
	v_mfma_f32_32x32x16_bf16 v[16:31], v[36:39], v[32:35], v[16:31]
	v_sub_f32_e32 v36, v45, v106
	v_exp_f32_e32 v45, v36
	v_sub_f32_e32 v36, v46, v106
	v_sub_f32_e32 v44, v44, v106
	v_exp_f32_e32 v46, v36
	v_sub_f32_e32 v36, v47, v106
	v_exp_f32_e32 v44, v44
	v_exp_f32_e32 v47, v36
	s_waitcnt lgkmcnt(0)
	v_mfma_f32_32x32x16_bf16 v[0:15], v[40:43], v[32:35], v[0:15]
	ds_read_b64_tr_b16 v[36:37], v137 offset:18432
	ds_read_b64_tr_b16 v[38:39], v137 offset:19968
	v_cvt_pk_bf16_f32 v32, v141, v52
	v_cvt_pk_bf16_f32 v33, v53, v54
	v_cvt_pk_bf16_f32 v34, v44, v45
	v_add_f32_e32 v105, v56, v105
	v_cvt_pk_bf16_f32 v35, v46, v47
	ds_read_b64_tr_b16 v[42:43], v137 offset:20032
	ds_read_b64_tr_b16 v[40:41], v137 offset:18496
	s_waitcnt lgkmcnt(2)
	v_mfma_f32_32x32x16_bf16 v[16:31], v[36:39], v[32:35], v[16:31]
	v_add_f32_e32 v36, v57, v105
	v_add_f32_e32 v36, v58, v36
	v_add_f32_e32 v36, v59, v36
	v_add_f32_e32 v36, v60, v36
	v_add_f32_e32 v36, v61, v36
	v_add_f32_e32 v36, v62, v36
	v_add_f32_e32 v36, v63, v36
	s_waitcnt lgkmcnt(0)
	v_mfma_f32_32x32x16_bf16 v[0:15], v[40:43], v[32:35], v[0:15]
	v_add_f32_e32 v32, v107, v36
	v_add_f32_e32 v32, v133, v32
	v_add_f32_e32 v32, v134, v32
	v_add_f32_e32 v32, v135, v32
	v_add_f32_e32 v32, v136, v32
	v_add_f32_e32 v32, v138, v32
	v_add_f32_e32 v32, v139, v32
	v_add_f32_e32 v32, v140, v32
	v_add_f32_e32 v32, v141, v32
	v_add_f32_e32 v32, v52, v32
	v_add_f32_e32 v32, v53, v32
	v_add_f32_e32 v32, v54, v32
	v_add_f32_e32 v32, v44, v32
	v_add_f32_e32 v32, v45, v32
	v_add_f32_e32 v32, v46, v32
	v_add_f32_e32 v105, v47, v32

; DI unsigned pack2(float a, float b) { return (unsigned)f2bf(a) | ((unsigned)f2bf(b) << 16); }
; DI f32x16 mfma32(bf16x8 a, bf16x8 b, f32x16 c) { return __builtin_amdgcn_mfma_f32_32x32x16_bf16(a, b, c, 0, 0, 0); }
; DI bf16x8 pack8(float a0, float a1, float a2, float a3, float a4, float a5, float a6, float a7) {
;   u32x4 p; p[0] = pack2(a0, a1); p[1] = pack2(a2, a3); p[2] = pack2(a4, a5); p[3] = pack2(a6, a7);
;   return __builtin_bit_cast(bf16x8, p);
; }
; template <bool MLA>
; DI void attn_task(const Params& p, char* smem, int b, int head, int qt) {
;     ...
; #pragma unroll
;       for (int k2 = 0; k2 < 2; ++k2)
; #pragma unroll
;         for (int i = 0; i < 16; ++i) { const float pv = __builtin_amdgcn_exp2f(s[k2][i] - mn); l += pv; s[k2][i] = pv; }
; #pragma unroll
;       for (int k2 = 0; k2 < 2; ++k2)
; #pragma unroll
;         for (int st = 0; st < 2; ++st) {
;           const bf16x8 pb = pack8(s[k2][8 * st + 0], s[k2][8 * st + 1], s[k2][8 * st + 2], s[k2][8 * st + 3],
;                                   s[k2][8 * st + 4], s[k2][8 * st + 5], s[k2][8 * st + 6], s[k2][8 * st + 7]);
; #pragma unroll
;           for (int dt = 0; dt < 2; ++dt) {
;             const bf16x8 va = frag_tr_perm(Vs, VLD, k2 * 32 + st * 16, dt * 32, lane);
;             oacc[dt] = mfma32(va, pb, oacc[dt]);
;           }
;         }
.LBB0_396:
	v_sub_f32_e32 v48, v48, v163
	v_exp_f32_e32 v48, v48
	v_sub_f32_e32 v49, v49, v163
	v_sub_f32_e32 v50, v50, v163
	v_exp_f32_e32 v49, v49
	v_exp_f32_e32 v50, v50
	v_sub_f32_e32 v51, v51, v163
	v_exp_f32_e32 v51, v51
	v_sub_f32_e32 v52, v52, v163
	v_sub_f32_e32 v32, v32, v163
	v_add_f32_e32 v162, v162, v48
	v_exp_f32_e32 v52, v52
	v_sub_f32_e32 v53, v53, v163
	v_exp_f32_e32 v164, v32
	v_sub_f32_e32 v32, v33, v163
	v_add_f32_e32 v162, v49, v162
	v_exp_f32_e32 v53, v53
	v_sub_f32_e32 v54, v54, v163
	v_exp_f32_e32 v165, v32
	v_sub_f32_e32 v32, v34, v163
	v_add_f32_e32 v162, v50, v162
	v_exp_f32_e32 v54, v54
	v_sub_f32_e32 v55, v55, v163
	v_exp_f32_e32 v166, v32
	v_sub_f32_e32 v32, v35, v163
	v_add_f32_e32 v162, v51, v162
	v_exp_f32_e32 v55, v55
	v_exp_f32_e32 v167, v32
	v_sub_f32_e32 v32, v36, v163
	v_add_f32_e32 v162, v52, v162
	v_exp_f32_e32 v168, v32
	v_cvt_pk_bf16_f32 v34, v51, s0
	v_add_u32_e32 v169, v119, v123
	v_add_f32_e32 v162, v53, v162
	v_cvt_pk_bf16_f32 v32, v48, v49
	v_cvt_pk_bf16_f32 v33, v50, s0
	v_lshlrev_b32_e32 v34, 16, v34
	ds_read_b64_tr_b16 v[48:49], v169 offset:13312
	ds_read_b64_tr_b16 v[50:51], v169 offset:14848
	v_add_f32_e32 v162, v54, v162
	v_or_b32_sdwa v33, v34, v33 dst_sel:DWORD dst_unused:UNUSED_PAD src0_sel:DWORD src1_sel:WORD_0
	v_add_f32_e32 v162, v55, v162
	v_sub_f32_e32 v57, v57, v163
	v_sub_f32_e32 v36, v37, v163
	v_cvt_pk_bf16_f32 v34, v52, v53
	v_cvt_pk_bf16_f32 v35, v54, s0
	v_cvt_pk_bf16_f32 v37, v55, s0
	ds_read_b64_tr_b16 v[54:55], v169 offset:14912
	ds_read_b64_tr_b16 v[52:53], v169 offset:13376
	v_sub_f32_e32 v56, v56, v163
	v_exp_f32_e32 v57, v57
	v_sub_f32_e32 v59, v59, v163
	v_lshlrev_b32_e32 v37, 16, v37
	v_exp_f32_e32 v56, v56
	v_sub_f32_e32 v58, v58, v163
	v_exp_f32_e32 v59, v59
	v_sub_f32_e32 v61, v61, v163
	v_or_b32_sdwa v35, v37, v35 dst_sel:DWORD dst_unused:UNUSED_PAD src0_sel:DWORD src1_sel:WORD_0
	v_exp_f32_e32 v58, v58
	v_sub_f32_e32 v60, v60, v163
	v_exp_f32_e32 v61, v61
	v_sub_f32_e32 v63, v63, v163
	s_waitcnt lgkmcnt(2)
	v_mfma_f32_32x32x16_bf16 v[16:31], v[48:51], v[32:35], v[16:31]
	v_exp_f32_e32 v170, v36
	v_sub_f32_e32 v36, v38, v163
	v_exp_f32_e32 v60, v60
	v_sub_f32_e32 v62, v62, v163
	v_exp_f32_e32 v63, v63
	v_exp_f32_e32 v171, v36
	v_sub_f32_e32 v36, v39, v163
	v_exp_f32_e32 v62, v62
	v_exp_f32_e32 v172, v36
	v_sub_f32_e32 v36, v40, v163
	s_waitcnt lgkmcnt(0)
	v_mfma_f32_32x32x16_bf16 v[0:15], v[52:55], v[32:35], v[0:15]
	v_exp_f32_e32 v173, v36
	ds_read_b64_tr_b16 v[36:37], v169 offset:16384
	ds_read_b64_tr_b16 v[38:39], v169 offset:17920
	v_cvt_pk_bf16_f32 v32, v56, v57
	v_cvt_pk_bf16_f32 v33, v58, v59
	ds_read_b64_tr_b16 v[50:51], v169 offset:17984
	ds_read_b64_tr_b16 v[48:49], v169 offset:16448
	v_cvt_pk_bf16_f32 v34, v60, v61
	v_cvt_pk_bf16_f32 v35, v62, v63
	s_waitcnt lgkmcnt(2)
	s_nop 0
	v_mfma_f32_32x32x16_bf16 v[16:31], v[36:39], v[32:35], v[16:31]
	v_sub_f32_e32 v36, v41, v163
	v_exp_f32_e32 v52, v36
	v_sub_f32_e32 v36, v42, v163
	v_exp_f32_e32 v53, v36
	v_sub_f32_e32 v36, v43, v163
	v_exp_f32_e32 v54, v36
	ds_read_b64_tr_b16 v[36:37], v169 offset:19456
	ds_read_b64_tr_b16 v[38:39], v169 offset:20992
	s_waitcnt lgkmcnt(2)
	v_mfma_f32_32x32x16_bf16 v[0:15], v[48:51], v[32:35], v[0:15]
	v_cvt_pk_bf16_f32 v32, v164, v165
	v_cvt_pk_bf16_f32 v33, v166, v167
	v_cvt_pk_bf16_f32 v34, v168, v170
	v_cvt_pk_bf16_f32 v35, v171, v172
	ds_read_b64_tr_b16 v[42:43], v169 offset:21056
	ds_read_b64_tr_b16 v[40:41], v169 offset:19520
	s_waitcnt lgkmcnt(2)
	v_mfma_f32_32x32x16_bf16 v[16:31], v[36:39], v[32:35], v[16:31]
	v_sub_f32_e32 v36, v45, v163
	v_exp_f32_e32 v45, v36
	v_sub_f32_e32 v36, v46, v163
	v_sub_f32_e32 v44, v44, v163
	v_exp_f32_e32 v46, v36
	v_sub_f32_e32 v36, v47, v163
	v_exp_f32_e32 v44, v44
	v_exp_f32_e32 v47, v36
	s_waitcnt lgkmcnt(0)
	v_mfma_f32_32x32x16_bf16 v[0:15], v[40:43], v[32:35], v[0:15]
	ds_read_b64_tr_b16 v[36:37], v169 offset:22528
	ds_read_b64_tr_b16 v[38:39], v169 offset:24064
	v_cvt_pk_bf16_f32 v32, v173, v52
	v_cvt_pk_bf16_f32 v33, v53, v54
	v_cvt_pk_bf16_f32 v34, v44, v45
	v_add_f32_e32 v162, v56, v162
	v_cvt_pk_bf16_f32 v35, v46, v47
	ds_read_b64_tr_b16 v[42:43], v169 offset:24128
	ds_read_b64_tr_b16 v[40:41], v169 offset:22592
	s_waitcnt lgkmcnt(2)
	v_mfma_f32_32x32x16_bf16 v[16:31], v[36:39], v[32:35], v[16:31]
	v_add_f32_e32 v36, v57, v162
	v_add_f32_e32 v36, v58, v36
	v_add_f32_e32 v36, v59, v36
	v_add_f32_e32 v36, v60, v36
	v_add_f32_e32 v36, v61, v36
	v_add_f32_e32 v36, v62, v36
	v_add_f32_e32 v36, v63, v36
	s_waitcnt lgkmcnt(0)
	v_mfma_f32_32x32x16_bf16 v[0:15], v[40:43], v[32:35], v[0:15]
	v_add_f32_e32 v32, v164, v36
	v_add_f32_e32 v32, v165, v32
	v_add_f32_e32 v32, v166, v32
	v_add_f32_e32 v32, v167, v32
	v_add_f32_e32 v32, v168, v32
	v_add_f32_e32 v32, v170, v32
	v_add_f32_e32 v32, v171, v32
	v_add_f32_e32 v32, v172, v32
	v_add_f32_e32 v32, v173, v32
	v_add_f32_e32 v32, v52, v32
	v_add_f32_e32 v32, v53, v32
	v_add_f32_e32 v32, v54, v32
	v_add_f32_e32 v32, v44, v32
	v_add_f32_e32 v32, v45, v32
	v_add_f32_e32 v32, v46, v32
	v_add_f32_e32 v162, v47, v32
